# attention phase: steal from one neighbour queue only, stage next K-V tile at step top, hand-pipelined P.V block (6 V fragments in flight); no drain before kinf atomics
# speedup vs baseline: 1.0076x; 1.0076x over previous
; __device__ __forceinline__ unsigned cvt_pk_bf16(float lo, float hi) { unsigned r; asm volatile("v_cvt_pk_bf16_f32 %0, %1, %2" : "=v"(r) : "v"(lo), "v"(hi)); return r; }
; #define PG8_GAS __attribute__((address_space(1)))
;     __device__ __forceinline__ void operator()(const f32x4 (&acc)[2][2][4][2], const Unit& u, int wr, int wc, int fr, int fq) const {
;     ...
;             const int cbase = ((seg == 0) ? 0 : (seg == 1) ? 512 : (seg == 3) ? 1024 : 1536) + 256 * half + wc * 32 + 8 * fq;
;             const float sc = (seg == 0 || seg == 3) ? qscale : 1.0f;
;             const int row0 = u.pm * BM + wr * 64 + fr;
; #pragma unroll
;             for (int ai = 0; ai < 2; ++ai)
; #pragma unroll
;                 for (int m = 0; m < 4; ++m) { bf16_t* rowp = QK + (size_t)(row0 + ai * HALF + m * 16) * 2048 + cbase;
; #pragma unroll
;                     for (int bj = 0; bj < 2; ++bj) { const f32x4 v0 = acc[ai][bj][m][0] * sc, v1 = acc[ai][bj][m][1] * sc;
;                         u32x4 w; w.x = cvt_pk_bf16(v0[0], v0[1]); w.y = cvt_pk_bf16(v0[2], v0[3]); w.z = cvt_pk_bf16(v1[0], v1[1]); w.w = cvt_pk_bf16(v1[2], v1[3]);
;                         *(PG8_GAS u32x4*)(rowp + bj * HALF) = w; } }
.LBB0_331:
	s_cmp_eq_u32 s35, 3
	s_cselect_b64 s[10:11], -1, 0
	s_and_b64 s[48:49], s[10:11], exec
	s_movk_i32 s3, 0x600
	s_cselect_b32 s3, 0x400, s3
	s_cmp_lg_u32 s35, 1
	s_cselect_b64 s[48:49], -1, 0
	s_and_b64 vcc, s[48:49], exec
	s_cselect_b32 s3, s3, 0x200
	s_cmp_lt_u32 s94, 2
	s_cselect_b64 s[48:49], -1, 0
	s_and_b64 s[60:61], s[48:49], exec
	s_cselect_b32 s3, 0, s3
	s_lshl_b32 s35, s31, 8
	s_or_b32 s3, s3, s35
	s_or_b64 s[10:11], s[48:49], s[10:11]
	v_ashrrev_i32_e32 v147, 31, v146
	v_or_b32_e32 v136, s3, v153
	v_cndmask_b32_e64 v148, 1.0, v164, s[10:11]
	v_lshlrev_b64 v[150:151], 12, v[146:147]
	v_lshl_add_u64 v[150:151], s[14:15], 0, v[150:151]
	v_lshlrev_b32_e32 v136, 1, v136
	v_pk_mul_f32 v[166:167], v[148:149], v[124:125] op_sel_hi:[0,1]
	v_lshl_add_u64 v[150:151], v[150:151], 0, v[136:137]
	v_pk_mul_f32 v[168:169], v[148:149], v[126:127] op_sel_hi:[0,1]
	v_cvt_pk_bf16_f32 v166, v166, v167
	v_cvt_pk_bf16_f32 v167, v168, v169
	v_pk_mul_f32 v[170:171], v[148:149], v[122:123] op_sel_hi:[0,1]
	v_pk_mul_f32 v[172:173], v[148:149], v[120:121] op_sel_hi:[0,1]
	v_cvt_pk_bf16_f32 v168, v172, v173
	v_cvt_pk_bf16_f32 v169, v170, v171
	global_store_dwordx4 v[150:151], v[166:169], off
	v_pk_mul_f32 v[170:171], v[148:149], v[110:111] op_sel_hi:[0,1]
	v_pk_mul_f32 v[172:173], v[148:149], v[108:109] op_sel_hi:[0,1]
	v_pk_mul_f32 v[166:167], v[148:149], v[116:117] op_sel_hi:[0,1]
	v_pk_mul_f32 v[168:169], v[148:149], v[118:119] op_sel_hi:[0,1]
	v_cvt_pk_bf16_f32 v166, v166, v167
	v_cvt_pk_bf16_f32 v167, v168, v169
	v_cvt_pk_bf16_f32 v168, v172, v173
	v_cvt_pk_bf16_f32 v169, v170, v171
	global_store_dwordx4 v[150:151], v[166:169], off offset:256
	v_pk_mul_f32 v[172:173], v[148:149], v[106:107] op_sel_hi:[0,1]
	v_pk_mul_f32 v[174:175], v[148:149], v[104:105] op_sel_hi:[0,1]
	v_or_b32_e32 v166, 16, v146
	v_ashrrev_i32_e32 v167, 31, v166
	v_lshlrev_b64 v[166:167], 12, v[166:167]
	v_lshl_add_u64 v[166:167], s[14:15], 0, v[166:167]
	v_lshl_add_u64 v[170:171], v[166:167], 0, v[136:137]
	v_pk_mul_f32 v[166:167], v[148:149], v[112:113] op_sel_hi:[0,1]
	v_pk_mul_f32 v[168:169], v[148:149], v[114:115] op_sel_hi:[0,1]
	v_cvt_pk_bf16_f32 v166, v166, v167
	v_cvt_pk_bf16_f32 v167, v168, v169
	v_cvt_pk_bf16_f32 v168, v174, v175
	v_cvt_pk_bf16_f32 v169, v172, v173
	global_store_dwordx4 v[170:171], v[166:169], off
	v_pk_mul_f32 v[172:173], v[148:149], v[94:95] op_sel_hi:[0,1]
	v_pk_mul_f32 v[174:175], v[148:149], v[92:93] op_sel_hi:[0,1]
	v_pk_mul_f32 v[166:167], v[148:149], v[100:101] op_sel_hi:[0,1]
	v_pk_mul_f32 v[168:169], v[148:149], v[102:103] op_sel_hi:[0,1]
	v_cvt_pk_bf16_f32 v166, v166, v167
	v_cvt_pk_bf16_f32 v167, v168, v169
	v_cvt_pk_bf16_f32 v168, v174, v175
	v_cvt_pk_bf16_f32 v169, v172, v173
	global_store_dwordx4 v[170:171], v[166:169], off offset:256
	v_pk_mul_f32 v[172:173], v[148:149], v[90:91] op_sel_hi:[0,1]
	v_pk_mul_f32 v[174:175], v[148:149], v[88:89] op_sel_hi:[0,1]
	v_or_b32_e32 v166, 32, v146
	v_ashrrev_i32_e32 v167, 31, v166
	v_lshlrev_b64 v[166:167], 12, v[166:167]
	v_lshl_add_u64 v[166:167], s[14:15], 0, v[166:167]
	v_lshl_add_u64 v[170:171], v[166:167], 0, v[136:137]
	v_pk_mul_f32 v[166:167], v[148:149], v[96:97] op_sel_hi:[0,1]
	v_pk_mul_f32 v[168:169], v[148:149], v[98:99] op_sel_hi:[0,1]
	v_cvt_pk_bf16_f32 v166, v166, v167
	v_cvt_pk_bf16_f32 v167, v168, v169
	v_cvt_pk_bf16_f32 v168, v174, v175
	v_cvt_pk_bf16_f32 v169, v172, v173
	global_store_dwordx4 v[170:171], v[166:169], off
	v_pk_mul_f32 v[172:173], v[148:149], v[78:79] op_sel_hi:[0,1]
	v_pk_mul_f32 v[174:175], v[148:149], v[76:77] op_sel_hi:[0,1]
	v_pk_mul_f32 v[166:167], v[148:149], v[84:85] op_sel_hi:[0,1]
	v_pk_mul_f32 v[168:169], v[148:149], v[86:87] op_sel_hi:[0,1]
	v_cvt_pk_bf16_f32 v166, v166, v167
	v_cvt_pk_bf16_f32 v167, v168, v169
	v_cvt_pk_bf16_f32 v168, v174, v175
	v_cvt_pk_bf16_f32 v169, v172, v173
	global_store_dwordx4 v[170:171], v[166:169], off offset:256
	v_pk_mul_f32 v[172:173], v[148:149], v[74:75] op_sel_hi:[0,1]
	v_pk_mul_f32 v[174:175], v[148:149], v[72:73] op_sel_hi:[0,1]
	v_or_b32_e32 v166, 48, v146
	v_ashrrev_i32_e32 v167, 31, v166
	v_lshlrev_b64 v[166:167], 12, v[166:167]
	v_lshl_add_u64 v[166:167], s[14:15], 0, v[166:167]
	v_lshl_add_u64 v[170:171], v[166:167], 0, v[136:137]
	v_pk_mul_f32 v[168:169], v[148:149], v[82:83] op_sel_hi:[0,1]
	v_pk_mul_f32 v[166:167], v[148:149], v[80:81] op_sel_hi:[0,1]
	v_cvt_pk_bf16_f32 v166, v166, v167
	v_cvt_pk_bf16_f32 v167, v168, v169
	v_cvt_pk_bf16_f32 v168, v174, v175
	v_cvt_pk_bf16_f32 v169, v172, v173
	global_store_dwordx4 v[170:171], v[166:169], off
	v_pk_mul_f32 v[172:173], v[148:149], v[66:67] op_sel_hi:[0,1]
	v_pk_mul_f32 v[174:175], v[148:149], v[64:65] op_sel_hi:[0,1]
	v_pk_mul_f32 v[168:169], v[148:149], v[70:71] op_sel_hi:[0,1]
	v_pk_mul_f32 v[166:167], v[148:149], v[68:69] op_sel_hi:[0,1]
	v_cvt_pk_bf16_f32 v166, v166, v167
	v_cvt_pk_bf16_f32 v167, v168, v169
	v_cvt_pk_bf16_f32 v168, v174, v175
	v_cvt_pk_bf16_f32 v169, v172, v173
	global_store_dwordx4 v[170:171], v[166:169], off offset:256
	s_mov_b64 s[10:11], 0x80000
	v_pk_mul_f32 v[172:173], v[148:149], v[58:59] op_sel_hi:[0,1]
	v_pk_mul_f32 v[168:169], v[148:149], v[62:63] op_sel_hi:[0,1]
	v_pk_mul_f32 v[166:167], v[148:149], v[60:61] op_sel_hi:[0,1]
	s_mov_b32 s3, 0x80000
	v_lshl_add_u64 v[170:171], v[150:151], 0, s[10:11]
	v_pk_mul_f32 v[174:175], v[148:149], v[56:57] op_sel_hi:[0,1]
	v_cvt_pk_bf16_f32 v166, v166, v167
	v_cvt_pk_bf16_f32 v167, v168, v169
	v_cvt_pk_bf16_f32 v168, v174, v175
	v_cvt_pk_bf16_f32 v169, v172, v173
	v_add_co_u32_e64 v172, s[10:11], s3, v150
	v_pk_mul_f32 v[174:175], v[148:149], v[44:45] op_sel_hi:[0,1]
	s_nop 0
; __device__ __forceinline__ unsigned cvt_pk_bf16(float lo, float hi) { unsigned r; asm volatile("v_cvt_pk_bf16_f32 %0, %1, %2" : "=v"(r) : "v"(lo), "v"(hi)); return r; }
; #define PG8_GAS __attribute__((address_space(1)))
;     __device__ __forceinline__ void operator()(const f32x4 (&acc)[2][2][4][2], const Unit& u, int wr, int wc, int fr, int fq) const {
;     ...
;                 for (int m = 0; m < 4; ++m) { bf16_t* rowp = QK + (size_t)(row0 + ai * HALF + m * 16) * 2048 + cbase;
; #pragma unroll
;                     for (int bj = 0; bj < 2; ++bj) { const f32x4 v0 = acc[ai][bj][m][0] * sc, v1 = acc[ai][bj][m][1] * sc;
;                         u32x4 w; w.x = cvt_pk_bf16(v0[0], v0[1]); w.y = cvt_pk_bf16(v0[2], v0[3]); w.z = cvt_pk_bf16(v1[0], v1[1]); w.w = cvt_pk_bf16(v1[2], v1[3]);
;                         *(PG8_GAS u32x4*)(rowp + bj * HALF) = w; } }
;             if (seg == 1) {
;                 const int b = (u.pm * BM) / S;
; #pragma unroll
;                 for (int bj = 0; bj < 2; ++bj) { float v = 0.f;
; #pragma unroll
;                     for (int ai = 0; ai < 2; ++ai)
; #pragma unroll
;                         for (int m = 0; m < 4; ++m) { const f32x4 x = acc[ai][bj][m][0], y = acc[ai][bj][m][1];
;                             float s2 = (x[0] * x[0] + x[1] * x[1]) + (x[2] * x[2] + x[3] * x[3]) + (y[0] * y[0] + y[1] * y[1]) + (y[2] * y[2] + y[3] * y[3]);
;                             s2 += __shfl_xor(s2, 16); s2 += __shfl_xor(s2, 32);
	v_addc_co_u32_e64 v173, s[10:11], 0, v151, s[10:11]
	global_store_dwordx4 v[172:173], v[166:169], off
	v_pk_mul_f32 v[172:173], v[148:149], v[46:47] op_sel_hi:[0,1]
	s_mov_b64 s[10:11], 0x90000
	v_pk_mul_f32 v[168:169], v[148:149], v[54:55] op_sel_hi:[0,1]
	v_pk_mul_f32 v[166:167], v[148:149], v[52:53] op_sel_hi:[0,1]
	v_cvt_pk_bf16_f32 v166, v166, v167
	v_cvt_pk_bf16_f32 v167, v168, v169
	v_cvt_pk_bf16_f32 v168, v174, v175
	v_cvt_pk_bf16_f32 v169, v172, v173
	global_store_dwordx4 v[170:171], v[166:169], off offset:256
	v_pk_mul_f32 v[172:173], v[148:149], v[42:43] op_sel_hi:[0,1]
	s_mov_b32 s3, 0x90000
	v_pk_mul_f32 v[168:169], v[148:149], v[50:51] op_sel_hi:[0,1]
	v_pk_mul_f32 v[166:167], v[148:149], v[48:49] op_sel_hi:[0,1]
	v_lshl_add_u64 v[170:171], v[150:151], 0, s[10:11]
	v_pk_mul_f32 v[174:175], v[148:149], v[40:41] op_sel_hi:[0,1]
	v_cvt_pk_bf16_f32 v166, v166, v167
	v_cvt_pk_bf16_f32 v167, v168, v169
	v_cvt_pk_bf16_f32 v168, v174, v175
	v_cvt_pk_bf16_f32 v169, v172, v173
	v_add_co_u32_e64 v172, s[10:11], s3, v150
	v_pk_mul_f32 v[174:175], v[148:149], v[28:29] op_sel_hi:[0,1]
	s_nop 0
	v_addc_co_u32_e64 v173, s[10:11], 0, v151, s[10:11]
	global_store_dwordx4 v[172:173], v[166:169], off
	v_pk_mul_f32 v[172:173], v[148:149], v[30:31] op_sel_hi:[0,1]
	s_nop 0
	v_pk_mul_f32 v[168:169], v[148:149], v[38:39] op_sel_hi:[0,1]
	v_pk_mul_f32 v[166:167], v[148:149], v[36:37] op_sel_hi:[0,1]
	v_cvt_pk_bf16_f32 v166, v166, v167
	v_cvt_pk_bf16_f32 v167, v168, v169
	v_cvt_pk_bf16_f32 v168, v174, v175
	v_cvt_pk_bf16_f32 v169, v172, v173
	global_store_dwordx4 v[170:171], v[166:169], off offset:256
	v_pk_mul_f32 v[172:173], v[148:149], v[26:27] op_sel_hi:[0,1]
	v_pk_mul_f32 v[174:175], v[148:149], v[24:25] op_sel_hi:[0,1]
	v_pk_mul_f32 v[168:169], v[148:149], v[34:35] op_sel_hi:[0,1]
	v_pk_mul_f32 v[166:167], v[148:149], v[32:33] op_sel_hi:[0,1]
	v_cvt_pk_bf16_f32 v166, v166, v167
	v_cvt_pk_bf16_f32 v167, v168, v169
	v_cvt_pk_bf16_f32 v168, v174, v175
	v_cvt_pk_bf16_f32 v169, v172, v173
	v_add_co_u32_e64 v172, s[10:11], s90, v150
	v_lshl_add_u64 v[170:171], v[150:151], 0, s[24:25]
	s_nop 0
	v_addc_co_u32_e64 v173, s[10:11], 0, v151, s[10:11]
	global_store_dwordx4 v[172:173], v[166:169], off
	v_pk_mul_f32 v[172:173], v[148:149], v[14:15] op_sel_hi:[0,1]
	v_pk_mul_f32 v[174:175], v[148:149], v[12:13] op_sel_hi:[0,1]
	v_pk_mul_f32 v[168:169], v[148:149], v[22:23] op_sel_hi:[0,1]
	v_pk_mul_f32 v[166:167], v[148:149], v[20:21] op_sel_hi:[0,1]
	v_cvt_pk_bf16_f32 v166, v166, v167
	v_cvt_pk_bf16_f32 v167, v168, v169
	v_cvt_pk_bf16_f32 v168, v174, v175
	v_cvt_pk_bf16_f32 v169, v172, v173
	global_store_dwordx4 v[170:171], v[166:169], off offset:256
	v_lshl_add_u64 v[170:171], v[150:151], 0, s[28:29]
	v_add_co_u32_e64 v150, s[10:11], s91, v150
	v_pk_mul_f32 v[168:169], v[148:149], v[18:19] op_sel_hi:[0,1]
	v_pk_mul_f32 v[166:167], v[148:149], v[16:17] op_sel_hi:[0,1]
	v_pk_mul_f32 v[172:173], v[148:149], v[10:11] op_sel_hi:[0,1]
	v_pk_mul_f32 v[174:175], v[148:149], v[8:9] op_sel_hi:[0,1]
	v_cvt_pk_bf16_f32 v166, v166, v167
	v_cvt_pk_bf16_f32 v167, v168, v169
	v_cvt_pk_bf16_f32 v168, v174, v175
	v_cvt_pk_bf16_f32 v169, v172, v173
	v_addc_co_u32_e64 v151, s[10:11], 0, v151, s[10:11]
	global_store_dwordx4 v[150:151], v[166:169], off
	v_pk_mul_f32 v[150:151], v[148:149], v[6:7] op_sel_hi:[0,1]
	v_pk_mul_f32 v[172:173], v[148:149], v[2:3] op_sel_hi:[0,1]
	v_pk_mul_f32 v[166:167], v[148:149], v[4:5] op_sel_hi:[0,1]
	v_pk_mul_f32 v[168:169], v[148:149], v[0:1] op_sel_hi:[0,1]
	v_cvt_pk_bf16_f32 v166, v166, v167
	v_cvt_pk_bf16_f32 v167, v150, v151
	v_cvt_pk_bf16_f32 v168, v168, v169
	v_cvt_pk_bf16_f32 v169, v172, v173
	global_store_dwordx4 v[170:171], v[166:169], off offset:256
	s_cbranch_vccnz .LBB0_337
	v_mul_f32_e32 v148, v125, v125
	v_mul_f32_e32 v150, v127, v127
	v_mul_f32_e32 v151, v113, v113
	v_mul_f32_e32 v167, v115, v115
	v_fmac_f32_e32 v148, v124, v124
	v_fmac_f32_e32 v150, v126, v126
	v_fmac_f32_e32 v151, v112, v112
	v_fmac_f32_e32 v167, v114, v114
	v_and_b32_e32 v147, 64, v165
	v_add_f32_e32 v148, v148, v150
	v_mul_f32_e32 v150, v121, v121
	v_add_f32_e32 v151, v151, v167
	v_mul_f32_e32 v167, v105, v105
	v_xor_b32_e32 v136, 16, v165
	v_add_u32_e32 v166, 64, v147
	v_fmac_f32_e32 v150, v120, v120
	v_fmac_f32_e32 v167, v104, v104
	v_cmp_lt_i32_e32 vcc, v136, v166
	v_add_f32_e32 v148, v148, v150
	v_mul_f32_e32 v150, v123, v123
	v_add_f32_e32 v151, v151, v167
	v_mul_f32_e32 v167, v107, v107
	v_cndmask_b32_e32 v136, v165, v136, vcc
	v_fmac_f32_e32 v150, v122, v122
	v_fmac_f32_e32 v167, v106, v106
	v_lshlrev_b32_e32 v136, 2, v136
	v_add_f32_e32 v148, v150, v148
	v_add_f32_e32 v151, v167, v151
	v_mul_f32_e32 v168, v97, v97
	v_mul_f32_e32 v169, v99, v99
	v_mul_f32_e32 v170, v81, v81
	v_mul_f32_e32 v171, v83, v83
	ds_bpermute_b32 v150, v136, v148
	ds_bpermute_b32 v167, v136, v151
	v_fmac_f32_e32 v168, v96, v96
	v_fmac_f32_e32 v169, v98, v98
	v_fmac_f32_e32 v170, v80, v80
	v_fmac_f32_e32 v171, v82, v82
	v_add_f32_e32 v168, v168, v169
	v_mul_f32_e32 v169, v89, v89
	v_add_f32_e32 v170, v170, v171
	v_mul_f32_e32 v171, v73, v73
	v_xor_b32_e32 v147, 32, v165
	v_fmac_f32_e32 v169, v88, v88
	v_fmac_f32_e32 v171, v72, v72
	v_cmp_lt_i32_e32 vcc, v147, v166
	v_add_f32_e32 v168, v168, v169
	v_mul_f32_e32 v169, v91, v91
	v_add_f32_e32 v170, v170, v171
	v_mul_f32_e32 v171, v75, v75
	v_cndmask_b32_e32 v147, v165, v147, vcc
	v_fmac_f32_e32 v169, v90, v90
	v_fmac_f32_e32 v171, v74, v74
	v_lshlrev_b32_e32 v147, 2, v147
	s_waitcnt lgkmcnt(0)
;     __device__ __forceinline__ void operator()(const f32x4 (&acc)[2][2][4][2], const Unit& u, int wr, int wc, int fr, int fq) const {
;     ...
;                 for (int bj = 0; bj < 2; ++bj) { float v = 0.f;
; #pragma unroll
;                     for (int ai = 0; ai < 2; ++ai)
; #pragma unroll
;                         for (int m = 0; m < 4; ++m) { const f32x4 x = acc[ai][bj][m][0], y = acc[ai][bj][m][1];
;                             float s2 = (x[0] * x[0] + x[1] * x[1]) + (x[2] * x[2] + x[3] * x[3]) + (y[0] * y[0] + y[1] * y[1]) + (y[2] * y[2] + y[3] * y[3]);
;                             s2 += __shfl_xor(s2, 16); s2 += __shfl_xor(s2, 32);
;                             v = fmaxf(v, s2); }
; #pragma unroll
;                     for (int o = 1; o < 16; o <<= 1) v = fmaxf(v, __shfl_xor(v, o));
;                     if (fr == 0 && fq == 0) atomicMax(kinf + (b * 8 + 4 * half + 2 * bj + (wc >> 1)) * 2 + (wc & 1), __float_as_uint(v)); }
	v_add_f32_e32 v148, v148, v150
	v_add_f32_e32 v151, v151, v167
	v_add_f32_e32 v168, v169, v168
	v_add_f32_e32 v170, v171, v170
	ds_bpermute_b32 v150, v147, v148
	ds_bpermute_b32 v167, v147, v151
	ds_bpermute_b32 v169, v136, v168
	ds_bpermute_b32 v171, v136, v170
	v_mul_f32_e32 v172, v19, v19
	s_waitcnt lgkmcnt(0)
	v_add_f32_e32 v148, v148, v150
	v_add_f32_e32 v150, v151, v167
	v_add_f32_e32 v151, v168, v169
	v_add_f32_e32 v168, v170, v171
	v_mul_f32_e32 v170, v61, v61
	v_mul_f32_e32 v171, v63, v63
	v_fmac_f32_e32 v170, v60, v60
	v_fmac_f32_e32 v171, v62, v62
	v_add_f32_e32 v170, v170, v171
	v_mul_f32_e32 v171, v57, v57
	v_fmac_f32_e32 v171, v56, v56
	v_add_f32_e32 v170, v170, v171
	v_mul_f32_e32 v171, v59, v59
	v_fmac_f32_e32 v171, v58, v58
	ds_bpermute_b32 v167, v147, v151
	ds_bpermute_b32 v169, v147, v168
	v_add_f32_e32 v170, v171, v170
	ds_bpermute_b32 v171, v136, v170
	v_max3_f32 v148, v148, 0, v150
	s_waitcnt lgkmcnt(0)
	v_add_f32_e32 v150, v151, v167
	v_add_f32_e32 v151, v168, v169
	v_mul_f32_e32 v167, v49, v49
	v_mul_f32_e32 v168, v51, v51
	v_max3_f32 v148, v148, v150, v151
	v_add_f32_e32 v150, v170, v171
	v_fmac_f32_e32 v167, v48, v48
	v_fmac_f32_e32 v168, v50, v50
	v_mul_f32_e32 v169, v33, v33
	v_mul_f32_e32 v170, v35, v35
	v_mul_f32_e32 v171, v17, v17
	v_add_f32_e32 v167, v167, v168
	v_mul_f32_e32 v168, v41, v41
	v_fmac_f32_e32 v169, v32, v32
	v_fmac_f32_e32 v170, v34, v34
	v_fmac_f32_e32 v171, v16, v16
	v_fmac_f32_e32 v172, v18, v18
	v_fmac_f32_e32 v168, v40, v40
	v_add_f32_e32 v169, v169, v170
	v_mul_f32_e32 v170, v25, v25
	v_add_f32_e32 v171, v171, v172
	v_mul_f32_e32 v172, v9, v9
	v_add_f32_e32 v167, v167, v168
	v_mul_f32_e32 v168, v43, v43
	v_fmac_f32_e32 v170, v24, v24
	v_fmac_f32_e32 v172, v8, v8
	v_fmac_f32_e32 v168, v42, v42
	v_add_f32_e32 v169, v169, v170
	v_mul_f32_e32 v170, v27, v27
	v_add_f32_e32 v171, v171, v172
	v_mul_f32_e32 v172, v11, v11
	v_add_f32_e32 v167, v168, v167
	v_fmac_f32_e32 v170, v26, v26
	v_fmac_f32_e32 v172, v10, v10
	ds_bpermute_b32 v168, v136, v167
	v_add_f32_e32 v169, v170, v169
	v_add_f32_e32 v171, v172, v171
	ds_bpermute_b32 v170, v136, v169
	ds_bpermute_b32 v172, v136, v171
	s_waitcnt lgkmcnt(0)
	v_add_f32_e32 v167, v167, v168
	ds_bpermute_b32 v151, v147, v150
	ds_bpermute_b32 v168, v147, v167
	v_add_f32_e32 v169, v169, v170
	v_add_f32_e32 v171, v171, v172
	ds_bpermute_b32 v170, v147, v169
	ds_bpermute_b32 v172, v147, v171
	s_waitcnt lgkmcnt(0)
	v_add_f32_e32 v150, v150, v151
	v_add_f32_e32 v151, v167, v168
	v_max3_f32 v148, v148, v150, v151
	v_add_f32_e32 v150, v169, v170
	v_add_f32_e32 v151, v171, v172
	v_max3_f32 v150, v148, v150, v151
	v_xor_b32_e32 v148, 1, v165
	v_cmp_lt_i32_e32 vcc, v148, v166
	s_ashr_i32 s3, s56, 31
	s_lshr_b32 s3, s3, 27
	v_cndmask_b32_e32 v148, v165, v148, vcc
	v_lshlrev_b32_e32 v148, 2, v148
	ds_bpermute_b32 v151, v148, v150
	s_add_i32 s3, s56, s3
	s_ashr_i32 s3, s3, 5
	s_lshl_b32 s3, s3, 4
	s_lshl_b32 s10, s31, 3
	s_waitcnt lgkmcnt(0)
	v_max_f32_e32 v151, v151, v151
	v_max_f32_e32 v151, v150, v151
	v_xor_b32_e32 v150, 2, v165
	v_cmp_lt_i32_e32 vcc, v150, v166
	s_or_b32 s3, s3, s10
	s_or_b32 s10, s3, s85
	v_cndmask_b32_e32 v150, v165, v150, vcc
	v_lshlrev_b32_e32 v150, 2, v150
	ds_bpermute_b32 v167, v150, v151
	s_waitcnt lgkmcnt(0)
	v_max_f32_e32 v167, v167, v167
	v_max_f32_e32 v167, v151, v167
	v_xor_b32_e32 v151, 4, v165
	v_cmp_lt_i32_e32 vcc, v151, v166
	s_nop 1
	v_cndmask_b32_e32 v151, v165, v151, vcc
	v_lshlrev_b32_e32 v151, 2, v151
	ds_bpermute_b32 v168, v151, v167
	s_waitcnt lgkmcnt(0)
	v_max_f32_e32 v168, v168, v168
	v_max_f32_e32 v167, v167, v168
	v_xor_b32_e32 v168, 8, v165
	v_cmp_lt_i32_e32 vcc, v168, v166
	s_nop 1
	v_cndmask_b32_e32 v166, v165, v168, vcc
	v_lshlrev_b32_e32 v166, 2, v166
	ds_bpermute_b32 v168, v166, v167
	s_and_saveexec_b64 s[60:61], s[6:7]
	s_cbranch_execz .LBB0_334
	s_ashr_i32 s11, s10, 31
	s_lshl_b64 s[48:49], s[10:11], 2
	s_add_u32 s48, s86, s48
	s_addc_u32 s49, s87, s49
	s_waitcnt lgkmcnt(0)
	v_max_f32_e32 v168, v168, v168
	v_max_f32_e32 v167, v167, v167
	v_max_f32_e32 v167, v167, v168
	v_mov_b64_e32 v[168:169], s[48:49]
	flat_atomic_umax v[168:169], v167
;     __device__ __forceinline__ void operator()(const f32x4 (&acc)[2][2][4][2], const Unit& u, int wr, int wc, int fr, int fq) const {
;     ...
;                 for (int bj = 0; bj < 2; ++bj) { float v = 0.f;
; #pragma unroll
;                     for (int ai = 0; ai < 2; ++ai)
; #pragma unroll
;                         for (int m = 0; m < 4; ++m) { const f32x4 x = acc[ai][bj][m][0], y = acc[ai][bj][m][1];
;                             float s2 = (x[0] * x[0] + x[1] * x[1]) + (x[2] * x[2] + x[3] * x[3]) + (y[0] * y[0] + y[1] * y[1]) + (y[2] * y[2] + y[3] * y[3]);
;                             s2 += __shfl_xor(s2, 16); s2 += __shfl_xor(s2, 32);
;                             v = fmaxf(v, s2); }
; #pragma unroll
;                     for (int o = 1; o < 16; o <<= 1) v = fmaxf(v, __shfl_xor(v, o));
;                     if (fr == 0 && fq == 0) atomicMax(kinf + (b * 8 + 4 * half + 2 * bj + (wc >> 1)) * 2 + (wc & 1), __float_as_uint(v)); }
.LBB0_334:
	s_or_b64 exec, exec, s[60:61]
	v_mul_f32_e32 v167, v117, v117
	s_waitcnt lgkmcnt(0)
	v_mul_f32_e32 v168, v119, v119
	v_mul_f32_e32 v169, v101, v101
	v_mul_f32_e32 v170, v103, v103
	v_fmac_f32_e32 v167, v116, v116
	v_fmac_f32_e32 v168, v118, v118
	v_fmac_f32_e32 v169, v100, v100
	v_fmac_f32_e32 v170, v102, v102
	v_add_f32_e32 v167, v167, v168
	v_mul_f32_e32 v168, v109, v109
	v_add_f32_e32 v169, v169, v170
	v_mul_f32_e32 v170, v93, v93
	v_fmac_f32_e32 v168, v108, v108
	v_fmac_f32_e32 v170, v92, v92
	v_add_f32_e32 v167, v167, v168
	v_mul_f32_e32 v168, v111, v111
	v_add_f32_e32 v169, v169, v170
	v_mul_f32_e32 v170, v95, v95
	v_fmac_f32_e32 v168, v110, v110
	v_fmac_f32_e32 v170, v94, v94
	v_add_f32_e32 v167, v168, v167
	v_add_f32_e32 v169, v170, v169
	v_mul_f32_e32 v171, v85, v85
	v_mul_f32_e32 v172, v87, v87
	v_mul_f32_e32 v173, v69, v69
	v_mul_f32_e32 v174, v71, v71
	ds_bpermute_b32 v168, v136, v167
	ds_bpermute_b32 v170, v136, v169
	v_fmac_f32_e32 v171, v84, v84
	v_fmac_f32_e32 v172, v86, v86
	v_fmac_f32_e32 v173, v68, v68
	v_fmac_f32_e32 v174, v70, v70
	v_add_f32_e32 v171, v171, v172
	v_mul_f32_e32 v172, v77, v77
	v_add_f32_e32 v173, v173, v174
	v_mul_f32_e32 v174, v65, v65
	v_fmac_f32_e32 v172, v76, v76
	v_fmac_f32_e32 v174, v64, v64
	v_add_f32_e32 v171, v171, v172
	v_mul_f32_e32 v172, v79, v79
	v_add_f32_e32 v173, v173, v174
	v_mul_f32_e32 v174, v67, v67
	v_fmac_f32_e32 v172, v78, v78
	v_fmac_f32_e32 v174, v66, v66
	s_waitcnt lgkmcnt(0)
	v_add_f32_e32 v167, v167, v168
	v_add_f32_e32 v169, v169, v170
	v_add_f32_e32 v171, v172, v171
	v_add_f32_e32 v173, v174, v173
	ds_bpermute_b32 v168, v147, v167
	ds_bpermute_b32 v170, v147, v169
	ds_bpermute_b32 v172, v136, v171
	ds_bpermute_b32 v174, v136, v173
	v_mul_f32_e32 v175, v7, v7
	s_waitcnt lgkmcnt(0)
	v_add_f32_e32 v167, v167, v168
	v_add_f32_e32 v168, v169, v170
	v_add_f32_e32 v169, v171, v172
	v_add_f32_e32 v171, v173, v174
	v_mul_f32_e32 v173, v53, v53
	v_mul_f32_e32 v174, v55, v55
	v_fmac_f32_e32 v173, v52, v52
	v_fmac_f32_e32 v174, v54, v54
	v_add_f32_e32 v173, v173, v174
	v_mul_f32_e32 v174, v45, v45
	v_fmac_f32_e32 v174, v44, v44
	v_add_f32_e32 v173, v173, v174
	v_mul_f32_e32 v174, v47, v47
	v_fmac_f32_e32 v174, v46, v46
	ds_bpermute_b32 v170, v147, v169
	ds_bpermute_b32 v172, v147, v171
	v_add_f32_e32 v173, v174, v173
	ds_bpermute_b32 v174, v136, v173
	v_max3_f32 v167, v167, 0, v168
	s_waitcnt lgkmcnt(0)
	v_add_f32_e32 v168, v169, v170
	v_add_f32_e32 v169, v171, v172
	v_mul_f32_e32 v170, v37, v37
	v_mul_f32_e32 v171, v39, v39
	v_max3_f32 v167, v167, v168, v169
	v_add_f32_e32 v168, v173, v174
	v_fmac_f32_e32 v170, v36, v36
	v_fmac_f32_e32 v171, v38, v38
	v_mul_f32_e32 v172, v21, v21
	v_mul_f32_e32 v173, v23, v23
	v_mul_f32_e32 v174, v5, v5
	v_add_f32_e32 v170, v170, v171
	v_mul_f32_e32 v171, v29, v29
	v_fmac_f32_e32 v172, v20, v20
	v_fmac_f32_e32 v173, v22, v22
	v_fmac_f32_e32 v174, v4, v4
	v_fmac_f32_e32 v175, v6, v6
	v_fmac_f32_e32 v171, v28, v28
	v_add_f32_e32 v172, v172, v173
	v_mul_f32_e32 v173, v13, v13
	v_add_f32_e32 v174, v174, v175
	v_mul_f32_e32 v175, v1, v1
	v_add_f32_e32 v170, v170, v171
	v_mul_f32_e32 v171, v31, v31
	v_fmac_f32_e32 v173, v12, v12
	v_fmac_f32_e32 v175, v0, v0
	v_fmac_f32_e32 v171, v30, v30
	v_add_f32_e32 v172, v172, v173
	v_mul_f32_e32 v173, v15, v15
	v_add_f32_e32 v174, v174, v175
	v_mul_f32_e32 v175, v3, v3
	v_add_f32_e32 v170, v171, v170
	v_fmac_f32_e32 v173, v14, v14
	v_fmac_f32_e32 v175, v2, v2
	ds_bpermute_b32 v171, v136, v170
	v_add_f32_e32 v172, v173, v172
	v_add_f32_e32 v174, v175, v174
	ds_bpermute_b32 v173, v136, v172
	ds_bpermute_b32 v136, v136, v174
	s_waitcnt lgkmcnt(0)
	v_add_f32_e32 v170, v170, v171
	ds_bpermute_b32 v169, v147, v168
	ds_bpermute_b32 v171, v147, v170
	v_add_f32_e32 v172, v172, v173
	v_add_f32_e32 v136, v174, v136
	ds_bpermute_b32 v173, v147, v172
	ds_bpermute_b32 v147, v147, v136
	s_waitcnt lgkmcnt(0)
	v_add_f32_e32 v168, v168, v169
	v_add_f32_e32 v169, v170, v171
	v_max3_f32 v167, v167, v168, v169
	v_add_f32_e32 v168, v172, v173
	v_add_f32_e32 v136, v136, v147
	v_max3_f32 v136, v167, v168, v136
	ds_bpermute_b32 v147, v148, v136
	s_waitcnt lgkmcnt(0)
	v_max_f32_e32 v147, v147, v147
	v_max_f32_e32 v136, v136, v147
	ds_bpermute_b32 v147, v150, v136
	s_waitcnt lgkmcnt(0)
	v_max_f32_e32 v147, v147, v147
	v_max_f32_e32 v136, v136, v147
	ds_bpermute_b32 v147, v151, v136
	s_waitcnt lgkmcnt(0)
	v_max_f32_e32 v147, v147, v147
	v_max_f32_e32 v136, v136, v147
	ds_bpermute_b32 v147, v166, v136
	s_and_saveexec_b64 s[60:61], s[6:7]
	s_cbranch_execz .LBB0_336
	s_ashr_i32 s11, s10, 31
	s_lshl_b64 s[10:11], s[10:11], 2
	s_add_u32 s10, s86, s10
	s_waitcnt lgkmcnt(0)
	v_max_f32_e32 v147, v147, v147
	v_max_f32_e32 v136, v136, v136
	s_addc_u32 s11, s87, s11
	v_max_f32_e32 v136, v136, v147
	v_mov_b64_e32 v[150:151], s[10:11]
	flat_atomic_umax v[150:151], v136 offset:16

; #define tid (fresh_tid())
; __global__ void __launch_bounds__(512) fwd_megakernel(Args args) {
;     ...
;         for (int qi = 0; qi < 8; ++qi) {
;             const unsigned xq = (myx + (unsigned)qi) & 7u;
;             unsigned* qctr = ctlw + CW_QUEUE + 64 * xq;
;             for (;;) {
;                 if (tid == 0) *uslot = atomicAdd(qctr, 1u);
;                 __syncthreads();
;                 const unsigned u = *uslot;
;                 __syncthreads();
;                 if (u >= 128u) break;
.LBB0_388:
	s_add_i32 s82, s82, 1
	s_cmp_eq_u32 s82, 2
	s_cbranch_scc1 .LBB0_435

; #define LAS __attribute__((address_space(3)))
; __device__ __forceinline__ int crow(int r, int hi) { return (r & 3) + 8 * (r >> 2) + 4 * hi; }
; #define MFMA32(a, b, c) __builtin_amdgcn_mfma_f32_32x32x16_bf16((a), (b), (c), 0, 0, 0)
; #define ATT_LOAD(set_, kt_) do { kreg[set_] = *(const GAS u32x4*)(ksrc + (size_t)(kt_) * 64 * 2048); \
;         _Pragma("unroll") for (int i_ = 0; i_ < NVC; ++i_) vreg[set_][i_] = *(const GAS u32x4*)(vsrc + (size_t)i_ * 64 * SEQ + (kt_) * 64); } while (0)
; #define ATT_STORE(set_, stg_) do { *(LAS u32x4*)(lds + (stg_) * STAGEB + kdst) = kreg[set_]; \
;         _Pragma("unroll") for (int i_ = 0; i_ < NVC; ++i_) *(LAS u32x4*)(lds + (stg_) * STAGEB + vdst + i_ * 64 * KSTR) = vreg[set_][i_]; } while (0)
; template <int MODE, int DV> ...
;     ...
;         ATT_LOAD(hh, (kt - 2 > 0) ? kt - 2 : 0);
;         const int k0 = kt * 64;
;         const LAS unsigned char* sb = lds + hh * STAGEB;
;         const bool active = ((MODE == 0) ? (k0 <= tw0 + 31) : (k0 < tw0 + 31)) && !wdone;
;         if (active) {
;             f32x16 p0, p1;
;             if (MODE == 0) {
;                 const float bb = slope2 * (float)(k0 + 4 * hi - t) - mrun;
; #pragma unroll
;                 for (int r = 0; r < 16; ++r) { const float c = __builtin_fmaf(slope2, (float)((r & 3) + 8 * (r >> 2)), bb); p0[r] = c; p1[r] = __builtin_fmaf(slope2, 32.0f, c); }
;             } else {
; #pragma unroll
;                 for (int r = 0; r < 16; ++r) { p0[r] = 0.f; p1[r] = 0.f; }
;             }
; #pragma unroll
;             for (int ds = 0; ds < 4; ++ds) {
;                 const bf16x8 k0f = *(const LAS bf16x8*)(sb + koff + ds * 32);
;                 const bf16x8 k1f = *(const LAS bf16x8*)(sb + koff + 32 * KSTR + ds * 32);
;                 p0 = MFMA32(k0f, qf[ds], p0); p1 = MFMA32(k1f, qf[ds], p1);
;             }
;             const bool diag = (MODE == 0) ? (k0 + 63 > tw0) : (k0 + 63 >= tw0);
;             bf16x8 pf0, pf1, pf2, pf3;
;             if (MODE == 0) {
;                 if (diag) {
; #pragma unroll
;                     for (int r = 0; r < 16; ++r) { const int key = k0 + crow(r, hi); if (key > t) p0[r] = -INFINITY; if (key + 32 > t) p1[r] = -INFINITY; }
;     ...
;         if (hasn) ATT_STORE(hh ^ 1, hh ^ 1);
.LBB0_399:
	s_max_i32 s3, s89, 2
	s_add_i32 s8, s3, -2
	s_lshl_b64 s[48:49], s[8:9], 18
	s_lshl_b32 s8, s8, 7
	s_waitcnt vmcnt(1)
	v_lshl_add_u64 v[6:7], v[148:149], 0, s[8:9]
	s_waitcnt vmcnt(0)
	s_cmp_lt_i32 s89, 1
	s_cbranch_scc1 .Lst_skip0
	ds_write_b128 v162, v[128:131] offset:27648
	ds_write_b128 v162, v[132:135] offset:36864
	ds_write_b128 v162, v[136:139] offset:46080
.Lst_skip0:
	v_add_co_u32_e32 v10, vcc, 0x100000, v6
	v_lshl_add_u64 v[2:3], v[146:147], 0, s[48:49]
	s_nop 0
	v_addc_co_u32_e32 v11, vcc, 0, v7, vcc
	global_load_dwordx4 v[2:5], v[2:3], off offset:1024
	s_nop 0
	global_load_dwordx4 v[6:9], v[6:7], off
	s_nop 0
	global_load_dwordx4 v[10:13], v[10:11], off
	s_lshl_b32 s8, s89, 6
	s_cmp_gt_i32 s8, s91
	s_cselect_b64 s[48:49], -1, 0
	s_or_b64 s[48:49], s[48:49], s[58:59]
	s_and_b64 vcc, exec, s[48:49]
	s_cbranch_vccnz .LBB0_410
	v_add_u32_e32 v0, s8, v166
	v_cvt_f32_i32_e32 v0, v0
	v_mov_b32_e32 v143, v142
	s_or_b32 s3, s8, 63
	s_cmp_le_i32 s3, s88
	v_fma_f32 v0, v142, v0, -v14
	v_fma_f32 v80, 0, v142, v0
	v_add_f32_e32 v81, v142, v0
	v_pk_fma_f32 v[82:83], v[152:153], s[12:13], v[0:1] op_sel_hi:[1,1,0]
	v_pk_fma_f32 v[84:85], v[152:153], s[14:15], v[0:1] op_sel_hi:[1,1,0]
	v_pk_fma_f32 v[86:87], v[152:153], s[16:17], v[0:1] op_sel_hi:[1,1,0]
	v_pk_fma_f32 v[88:89], v[152:153], s[18:19], v[0:1] op_sel_hi:[1,1,0]
	v_pk_fma_f32 v[90:91], v[152:153], s[20:21], v[0:1] op_sel_hi:[1,1,0]
	v_pk_fma_f32 v[92:93], v[152:153], s[22:23], v[0:1] op_sel_hi:[1,1,0]
	v_pk_fma_f32 v[94:95], v[152:153], s[24:25], v[0:1] op_sel_hi:[1,1,0]
	v_add_u32_e32 v0, 0, v163
	ds_read_b128 v[170:173], v0
	ds_read_b128 v[174:177], v0 offset:32
	v_pk_fma_f32 v[110:111], v[142:143], s[28:29], v[94:95] op_sel_hi:[1,0,1]
	v_pk_fma_f32 v[108:109], v[142:143], s[28:29], v[92:93] op_sel_hi:[1,0,1]
	v_pk_fma_f32 v[106:107], v[142:143], s[28:29], v[90:91] op_sel_hi:[1,0,1]
	v_pk_fma_f32 v[104:105], v[142:143], s[28:29], v[88:89] op_sel_hi:[1,0,1]
	v_pk_fma_f32 v[102:103], v[142:143], s[28:29], v[86:87] op_sel_hi:[1,0,1]
	v_pk_fma_f32 v[100:101], v[142:143], s[28:29], v[84:85] op_sel_hi:[1,0,1]
	v_pk_fma_f32 v[98:99], v[142:143], s[28:29], v[82:83] op_sel_hi:[1,0,1]
	v_pk_fma_f32 v[96:97], v[154:155], s[28:29], v[80:81] op_sel_hi:[1,0,1]
	s_waitcnt lgkmcnt(1)
	v_mfma_f32_32x32x16_bf16 v[80:95], v[170:173], v[112:115], v[80:95]
	ds_read_b128 v[170:173], v0 offset:4608
	ds_read_b128 v[178:181], v0 offset:4640
	s_waitcnt lgkmcnt(1)
	v_mfma_f32_32x32x16_bf16 v[96:111], v[170:173], v[112:115], v[96:111]
	v_mfma_f32_32x32x16_bf16 v[80:95], v[174:177], v[116:119], v[80:95]
	ds_read_b128 v[170:173], v0 offset:64
	ds_read_b128 v[174:177], v0 offset:96
	s_waitcnt lgkmcnt(2)
	v_mfma_f32_32x32x16_bf16 v[96:111], v[178:181], v[116:119], v[96:111]
	s_waitcnt lgkmcnt(1)
	v_mfma_f32_32x32x16_bf16 v[80:95], v[170:173], v[120:123], v[80:95]
	ds_read_b128 v[170:173], v0 offset:4672
	ds_read_b128 v[178:181], v0 offset:4704
	s_waitcnt lgkmcnt(1)
	v_mfma_f32_32x32x16_bf16 v[96:111], v[170:173], v[120:123], v[96:111]
	v_mfma_f32_32x32x16_bf16 v[80:95], v[174:177], v[124:127], v[80:95]
	s_waitcnt lgkmcnt(0)
	v_mfma_f32_32x32x16_bf16 v[96:111], v[178:181], v[124:127], v[96:111]
	s_cbranch_scc1 .LBB0_402
	v_or_b32_e32 v15, s8, v165
	v_or_b32_e32 v143, 32, v15
	v_cmp_le_i32_e32 vcc, v143, v140
	v_or_b32_e32 v143, 33, v15
	s_nop 6
	v_cndmask_b32_e32 v96, v159, v96, vcc
	v_cmp_lt_i32_e32 vcc, v15, v140
	s_nop 1
	v_cndmask_b32_e32 v81, v159, v81, vcc
	v_cmp_le_i32_e32 vcc, v15, v140
	s_nop 1
	v_cndmask_b32_e32 v80, v159, v80, vcc
	v_cmp_le_i32_e32 vcc, v143, v140
	v_or_b32_e32 v143, 2, v15
	s_nop 0
	v_cndmask_b32_e32 v97, v159, v97, vcc
	v_cmp_le_i32_e32 vcc, v143, v140
	v_or_b32_e32 v143, 34, v15
	s_nop 0
	v_cndmask_b32_e32 v82, v159, v82, vcc
	v_cmp_le_i32_e32 vcc, v143, v140
	v_or_b32_e32 v143, 3, v15
	s_nop 0
	v_cndmask_b32_e32 v98, v159, v98, vcc
	v_cmp_le_i32_e32 vcc, v143, v140
	v_or_b32_e32 v143, 35, v15
	s_nop 0
	v_cndmask_b32_e32 v83, v159, v83, vcc
	v_cmp_le_i32_e32 vcc, v143, v140
	v_or_b32_e32 v143, 8, v15
	s_nop 0
	v_cndmask_b32_e32 v99, v159, v99, vcc
	v_cmp_le_i32_e32 vcc, v143, v140
	v_or_b32_e32 v143, 40, v15
	s_nop 0
	v_cndmask_b32_e32 v84, v159, v84, vcc
	v_cmp_le_i32_e32 vcc, v143, v140
	v_or_b32_e32 v143, 9, v15
	s_nop 0
	v_cndmask_b32_e32 v100, v159, v100, vcc
	v_cmp_le_i32_e32 vcc, v143, v140
	v_or_b32_e32 v143, 41, v15
	s_nop 0
	v_cndmask_b32_e32 v85, v159, v85, vcc
	v_cmp_le_i32_e32 vcc, v143, v140
	v_or_b32_e32 v143, 10, v15
	s_nop 0
	v_cndmask_b32_e32 v101, v159, v101, vcc
	v_cmp_le_i32_e32 vcc, v143, v140
	v_or_b32_e32 v143, 42, v15
	s_nop 0
	v_cndmask_b32_e32 v86, v159, v86, vcc
	v_cmp_le_i32_e32 vcc, v143, v140
	v_or_b32_e32 v143, 11, v15
	s_nop 0
	v_cndmask_b32_e32 v102, v159, v102, vcc
	v_cmp_le_i32_e32 vcc, v143, v140
	v_or_b32_e32 v143, 43, v15
	s_nop 0
	v_cndmask_b32_e32 v87, v159, v87, vcc
	v_cmp_le_i32_e32 vcc, v143, v140
	v_or_b32_e32 v143, 16, v15
	s_nop 0
	v_cndmask_b32_e32 v103, v159, v103, vcc
	v_cmp_le_i32_e32 vcc, v143, v140
	v_or_b32_e32 v143, 48, v15
	s_nop 0
	v_cndmask_b32_e32 v88, v159, v88, vcc
	v_cmp_le_i32_e32 vcc, v143, v140
	v_or_b32_e32 v143, 17, v15
	s_nop 0
	v_cndmask_b32_e32 v104, v159, v104, vcc
	v_cmp_le_i32_e32 vcc, v143, v140
	v_or_b32_e32 v143, 49, v15
	s_nop 0
	v_cndmask_b32_e32 v89, v159, v89, vcc
	v_cmp_le_i32_e32 vcc, v143, v140
	v_or_b32_e32 v143, 18, v15
	s_nop 0
	v_cndmask_b32_e32 v105, v159, v105, vcc
	v_cmp_le_i32_e32 vcc, v143, v140
	v_or_b32_e32 v143, 50, v15
	s_nop 0
	v_cndmask_b32_e32 v90, v159, v90, vcc
	v_cmp_le_i32_e32 vcc, v143, v140
	v_or_b32_e32 v143, 19, v15
	s_nop 0
	v_cndmask_b32_e32 v106, v159, v106, vcc
	v_cmp_le_i32_e32 vcc, v143, v140
	v_or_b32_e32 v143, 51, v15
	s_nop 0
	v_cndmask_b32_e32 v91, v159, v91, vcc
	v_cmp_le_i32_e32 vcc, v143, v140
	v_or_b32_e32 v143, 24, v15
	s_nop 0
	v_cndmask_b32_e32 v107, v159, v107, vcc
	v_cmp_le_i32_e32 vcc, v143, v140
	v_or_b32_e32 v143, 56, v15
	s_nop 0
	v_cndmask_b32_e32 v92, v159, v92, vcc
	v_cmp_le_i32_e32 vcc, v143, v140
	v_or_b32_e32 v143, 25, v15
	s_nop 0
	v_cndmask_b32_e32 v108, v159, v108, vcc
	v_cmp_le_i32_e32 vcc, v143, v140
	v_or_b32_e32 v143, 57, v15
	s_nop 0
	v_cndmask_b32_e32 v93, v159, v93, vcc
	v_cmp_le_i32_e32 vcc, v143, v140
	v_or_b32_e32 v143, 26, v15
	s_nop 0
	v_cndmask_b32_e32 v109, v159, v109, vcc
	v_cmp_le_i32_e32 vcc, v143, v140
	v_or_b32_e32 v143, 58, v15
	s_nop 0
	v_cndmask_b32_e32 v94, v159, v94, vcc
	v_cmp_le_i32_e32 vcc, v143, v140
	v_or_b32_e32 v143, 27, v15
	v_or_b32_e32 v15, 59, v15
	v_cndmask_b32_e32 v110, v159, v110, vcc
	v_cmp_le_i32_e32 vcc, v143, v140
	s_nop 1
	v_cndmask_b32_e32 v95, v159, v95, vcc
	v_cmp_le_i32_e32 vcc, v15, v140
	s_nop 1
	v_cndmask_b32_e32 v111, v159, v111, vcc

; #define LAS __attribute__((address_space(3)))
; #define MFMA32(a, b, c) __builtin_amdgcn_mfma_f32_32x32x16_bf16((a), (b), (c), 0, 0, 0)
; #define ATT_STORE(set_, stg_) do { *(LAS u32x4*)(lds + (stg_) * STAGEB + kdst) = kreg[set_]; \
;         _Pragma("unroll") for (int i_ = 0; i_ < NVC; ++i_) *(LAS u32x4*)(lds + (stg_) * STAGEB + vdst + i_ * 64 * KSTR) = vreg[set_][i_]; } while (0)
; #define ATT_STORE(set_, stg_) do { _Pragma("unroll") for (int i_ = 0; i_ < 2; ++i_) { *(LAS u32x4*)(lds + (stg_) * SB2_STAGE + kdst + i_ * 32 * KSTR) = kreg[set_][i_]; \
;         *(LAS u32x4*)(lds + (stg_) * SB2_STAGE + vdst + i_ * 32 * KSTR) = vreg[set_][i_]; } } while (0)
; template <int MODE, int DV> ...
;     ...
; #pragma unroll
;                 for (int r = 0; r < 16; ++r) { p0[r] = __builtin_amdgcn_exp2f(p0[r]); p1[r] = __builtin_amdgcn_exp2f(p1[r]); }
;                 { float s0 = p0[0] + p1[0], s1 = p0[1] + p1[1], s2 = p0[2] + p1[2], s3 = p0[3] + p1[3];
; #pragma unroll
;                   for (int r = 4; r < 16; r += 4) { s0 += p0[r] + p1[r]; s1 += p0[r + 1] + p1[r + 1]; s2 += p0[r + 2] + p1[r + 2]; s3 += p0[r + 3] + p1[r + 3]; }
;                   lrun += (s0 + s1) + (s2 + s3); }
;                 pf0 = pack8(p0, 0); pf1 = pack8(p0, 8); pf2 = pack8(p1, 0); pf3 = pack8(p1, 8);
;     ...
;             for (int d = 0; d < NDB; ++d) {
;                 const LAS unsigned char* vb = sb + KBUFB + d * 32 * KSTR + koff;
;                 const bf16x8 v0 = *(const LAS bf16x8*)(vb), v1 = *(const LAS bf16x8*)(vb + 32), v2 = *(const LAS bf16x8*)(vb + 64), v3 = *(const LAS bf16x8*)(vb + 96);
;                 o[d] = MFMA32(v0, pf0, o[d]); o[d] = MFMA32(v1, pf1, o[d]); o[d] = MFMA32(v2, pf2, o[d]); o[d] = MFMA32(v3, pf3, o[d]);
;             }
;         }
;         if (hasn) ATT_STORE(hh ^ 1, hh ^ 1);
;         if (lane == 0) flags[hh * 8 + wid] = wdone ? 1u : 0u;
;         __syncthreads();
;         if (!hasn) { fin = true; break; }
;         { const unsigned f = flags[hh * 8 + (lane & 7)]; if (__all(f != 0u)) { fin = true; break; } }
.LBB0_409:
	ds_read_b128 v[212:215], v163 offset:9216
	ds_read_b128 v[216:219], v163 offset:9248
	ds_read_b128 v[220:223], v163 offset:9280
	ds_read_b128 v[224:227], v163 offset:9312
	ds_read_b128 v[228:231], v163 offset:13824
	ds_read_b128 v[232:235], v163 offset:13856
	v_exp_f32_e32 v80, v80
	v_exp_f32_e32 v81, v81
	v_exp_f32_e32 v82, v82
	v_exp_f32_e32 v83, v83
	v_exp_f32_e32 v84, v84
	v_exp_f32_e32 v85, v85
	v_exp_f32_e32 v86, v86
	v_exp_f32_e32 v87, v87
	v_cvt_pk_bf16_f32 v196, v80, v81
	v_cvt_pk_bf16_f32 v197, v82, v83
	v_cvt_pk_bf16_f32 v198, v84, v85
	v_cvt_pk_bf16_f32 v199, v86, v87
	s_waitcnt lgkmcnt(5)
	s_nop 0
	v_mfma_f32_32x32x16_bf16 v[64:79], v[212:215], v[196:199], v[64:79]
	ds_read_b128 v[212:215], v163 offset:13888
	v_exp_f32_e32 v88, v88
	v_exp_f32_e32 v89, v89
	v_exp_f32_e32 v90, v90
	v_exp_f32_e32 v91, v91
	v_exp_f32_e32 v92, v92
	v_exp_f32_e32 v93, v93
	v_exp_f32_e32 v94, v94
	v_exp_f32_e32 v95, v95
	v_cvt_pk_bf16_f32 v200, v88, v89
	v_cvt_pk_bf16_f32 v201, v90, v91
	v_cvt_pk_bf16_f32 v202, v92, v93
	v_cvt_pk_bf16_f32 v203, v94, v95
	s_waitcnt lgkmcnt(5)
	s_nop 0
	v_mfma_f32_32x32x16_bf16 v[64:79], v[216:219], v[200:203], v[64:79]
	ds_read_b128 v[216:219], v163 offset:13920
	v_exp_f32_e32 v96, v96
	v_exp_f32_e32 v97, v97
	v_exp_f32_e32 v98, v98
	v_exp_f32_e32 v99, v99
	v_exp_f32_e32 v100, v100
	v_exp_f32_e32 v101, v101
	v_exp_f32_e32 v102, v102
	v_exp_f32_e32 v103, v103
	v_cvt_pk_bf16_f32 v204, v96, v97
	v_cvt_pk_bf16_f32 v205, v98, v99
	v_cvt_pk_bf16_f32 v206, v100, v101
	v_cvt_pk_bf16_f32 v207, v102, v103
	s_waitcnt lgkmcnt(5)
	s_nop 0
	v_mfma_f32_32x32x16_bf16 v[64:79], v[220:223], v[204:207], v[64:79]
	ds_read_b128 v[220:223], v163 offset:18432
	v_exp_f32_e32 v104, v104
	v_exp_f32_e32 v105, v105
	v_exp_f32_e32 v106, v106
	v_exp_f32_e32 v107, v107
	v_exp_f32_e32 v108, v108
	v_exp_f32_e32 v109, v109
	v_exp_f32_e32 v110, v110
	v_exp_f32_e32 v111, v111
	v_cvt_pk_bf16_f32 v208, v104, v105
	v_cvt_pk_bf16_f32 v209, v106, v107
	v_cvt_pk_bf16_f32 v210, v108, v109
	v_cvt_pk_bf16_f32 v211, v110, v111
	s_waitcnt lgkmcnt(5)
	s_nop 0
	v_mfma_f32_32x32x16_bf16 v[64:79], v[224:227], v[208:211], v[64:79]
	ds_read_b128 v[224:227], v163 offset:18464
	s_waitcnt lgkmcnt(5)
	v_mfma_f32_32x32x16_bf16 v[48:63], v[228:231], v[196:199], v[48:63]
	ds_read_b128 v[228:231], v163 offset:18496
	v_add_f32_e32 v170, v80, v96
	v_add_f32_e32 v171, v81, v97
	v_add_f32_e32 v172, v82, v98
	s_waitcnt lgkmcnt(5)
	v_mfma_f32_32x32x16_bf16 v[48:63], v[232:235], v[200:203], v[48:63]
	ds_read_b128 v[232:235], v163 offset:18528
	v_add_f32_e32 v173, v83, v99
	v_add_f32_e32 v174, v84, v100
	v_add_f32_e32 v175, v85, v101
	s_waitcnt lgkmcnt(5)
	v_mfma_f32_32x32x16_bf16 v[48:63], v[212:215], v[204:207], v[48:63]
	ds_read_b128 v[212:215], v163 offset:23040
	v_add_f32_e32 v176, v86, v102
	v_add_f32_e32 v177, v87, v103
	v_add_f32_e32 v170, v170, v174
	s_waitcnt lgkmcnt(5)
	v_mfma_f32_32x32x16_bf16 v[48:63], v[216:219], v[208:211], v[48:63]
	ds_read_b128 v[216:219], v163 offset:23072
	v_add_f32_e32 v171, v171, v175
	v_add_f32_e32 v172, v172, v176
	v_add_f32_e32 v173, v173, v177
	s_waitcnt lgkmcnt(5)
	v_mfma_f32_32x32x16_bf16 v[32:47], v[220:223], v[196:199], v[32:47]
	ds_read_b128 v[220:223], v163 offset:23104
	v_add_f32_e32 v174, v88, v104
	v_add_f32_e32 v175, v89, v105
	v_add_f32_e32 v176, v90, v106
	s_waitcnt lgkmcnt(5)
	v_mfma_f32_32x32x16_bf16 v[32:47], v[224:227], v[200:203], v[32:47]
	ds_read_b128 v[224:227], v163 offset:23136
	v_add_f32_e32 v177, v91, v107
	v_add_f32_e32 v170, v170, v174
	v_add_f32_e32 v171, v171, v175
	s_waitcnt lgkmcnt(5)
	v_mfma_f32_32x32x16_bf16 v[32:47], v[228:231], v[204:207], v[32:47]
	v_add_f32_e32 v172, v172, v176
	v_add_f32_e32 v173, v173, v177
	v_add_f32_e32 v174, v92, v108
	s_waitcnt lgkmcnt(4)
	v_mfma_f32_32x32x16_bf16 v[32:47], v[232:235], v[208:211], v[32:47]
	v_add_f32_e32 v175, v93, v109
	v_add_f32_e32 v176, v94, v110
	v_add_f32_e32 v177, v95, v111
	s_waitcnt lgkmcnt(3)
	v_mfma_f32_32x32x16_bf16 v[16:31], v[212:215], v[196:199], v[16:31]
	v_add_f32_e32 v170, v170, v174
	v_add_f32_e32 v171, v171, v175
	v_add_f32_e32 v172, v172, v176
	s_waitcnt lgkmcnt(2)
	v_mfma_f32_32x32x16_bf16 v[16:31], v[216:219], v[200:203], v[16:31]
	v_add_f32_e32 v173, v173, v177
	v_add_f32_e32 v170, v170, v171
	v_add_f32_e32 v172, v172, v173
	s_waitcnt lgkmcnt(1)
	v_mfma_f32_32x32x16_bf16 v[16:31], v[220:223], v[204:207], v[16:31]
	v_add_f32_e32 v170, v170, v172
	v_add_f32_e32 v168, v168, v170
	v_subrev_u32_e32 v15, s8, v167
	s_waitcnt lgkmcnt(0)
	v_mfma_f32_32x32x16_bf16 v[16:31], v[224:227], v[208:211], v[16:31]
	v_cvt_f32_i32_e32 v15, v15
	v_fma_f32 v0, -v142, v15, v161
	v_add_f32_e32 v15, 0xc2000000, v14
	v_cmp_lt_f32_e32 vcc, v0, v15
	s_cmp_eq_u64 vcc, exec
	s_cselect_b64 s[58:59], -1, 0
	s_mov_b64 s[6:7], 0
.LBB0_410:
	s_cmp_gt_i32 s89, 0
	s_cselect_b64 s[56:57], -1, 0
	s_cmp_lt_i32 s89, 1
	s_cbranch_scc1 .LBB0_412
.LBB0_412:
	s_and_saveexec_b64 s[60:61], s[4:5]
	v_cndmask_b32_e64 v0, 0, 1, s[58:59]
	v_mov_b32_e32 v15, s90
	ds_write_b32 v15, v0 offset:55296
	s_or_b64 exec, exec, s[60:61]
	s_andn2_b64 vcc, exec, s[56:57]
	s_waitcnt lgkmcnt(0)
	s_barrier
	s_cbranch_vccnz .LBB0_416
	ds_read_b32 v0, v164 offset:55296
	s_waitcnt lgkmcnt(0)
	v_cmp_ne_u32_e32 vcc, 0, v0
	s_cmp_eq_u64 vcc, exec
	s_cselect_b64 s[56:57], -1, 0
	s_cmp_lg_u64 vcc, exec
	s_cselect_b64 s[60:61], -1, 0
	s_cmp_lg_u64 s[60:61], 0
	s_subb_u32 s89, s89, 0
	s_andn2_b64 vcc, exec, s[60:61]
	s_cbranch_vccnz .LBB0_398
	s_branch .LBB0_417

; #define ATT_STORE(set_, stg_) do { *(LAS u32x4*)(lds + (stg_) * STAGEB + kdst) = kreg[set_]; \
;         _Pragma("unroll") for (int i_ = 0; i_ < NVC; ++i_) *(LAS u32x4*)(lds + (stg_) * STAGEB + vdst + i_ * 64 * KSTR) = vreg[set_][i_]; } while (0)
; #define ATT_STORE(set_, stg_) do { _Pragma("unroll") for (int i_ = 0; i_ < 2; ++i_) { *(LAS u32x4*)(lds + (stg_) * SB2_STAGE + kdst + i_ * 32 * KSTR) = kreg[set_][i_]; \
;         *(LAS u32x4*)(lds + (stg_) * SB2_STAGE + vdst + i_ * 32 * KSTR) = vreg[set_][i_]; } } while (0)
; template <int MODE, int DV> ...
;     ...
;         if (hasn) ATT_STORE(hh ^ 1, hh ^ 1);
.LBB0_417:
	s_cmp_lt_i32 s89, 1
	s_cbranch_scc1 .Lst_skip1
	s_waitcnt vmcnt(0)
	ds_write_b128 v162, v[2:5]
	ds_write_b128 v162, v[6:9] offset:9216
	ds_write_b128 v162, v[10:13] offset:18432

; #define LAS __attribute__((address_space(3)))
; #define MFMA32(a, b, c) __builtin_amdgcn_mfma_f32_32x32x16_bf16((a), (b), (c), 0, 0, 0)
; #define ATT_STORE(set_, stg_) do { *(LAS u32x4*)(lds + (stg_) * STAGEB + kdst) = kreg[set_]; \
;         _Pragma("unroll") for (int i_ = 0; i_ < NVC; ++i_) *(LAS u32x4*)(lds + (stg_) * STAGEB + vdst + i_ * 64 * KSTR) = vreg[set_][i_]; } while (0)
; #define ATT_STORE(set_, stg_) do { _Pragma("unroll") for (int i_ = 0; i_ < 2; ++i_) { *(LAS u32x4*)(lds + (stg_) * SB2_STAGE + kdst + i_ * 32 * KSTR) = kreg[set_][i_]; \
;         *(LAS u32x4*)(lds + (stg_) * SB2_STAGE + vdst + i_ * 32 * KSTR) = vreg[set_][i_]; } } while (0)
; template <int MODE, int DV> ...
;     ...
; #pragma unroll
;                 for (int r = 0; r < 16; ++r) { p0[r] = __builtin_amdgcn_exp2f(p0[r]); p1[r] = __builtin_amdgcn_exp2f(p1[r]); }
;                 { float s0 = p0[0] + p1[0], s1 = p0[1] + p1[1], s2 = p0[2] + p1[2], s3 = p0[3] + p1[3];
; #pragma unroll
;                   for (int r = 4; r < 16; r += 4) { s0 += p0[r] + p1[r]; s1 += p0[r + 1] + p1[r + 1]; s2 += p0[r + 2] + p1[r + 2]; s3 += p0[r + 3] + p1[r + 3]; }
;                   lrun += (s0 + s1) + (s2 + s3); }
;                 pf0 = pack8(p0, 0); pf1 = pack8(p0, 8); pf2 = pack8(p1, 0); pf3 = pack8(p1, 8);
;     ...
;             for (int d = 0; d < NDB; ++d) {
;                 const LAS unsigned char* vb = sb + KBUFB + d * 32 * KSTR + koff;
;                 const bf16x8 v0 = *(const LAS bf16x8*)(vb), v1 = *(const LAS bf16x8*)(vb + 32), v2 = *(const LAS bf16x8*)(vb + 64), v3 = *(const LAS bf16x8*)(vb + 96);
;                 o[d] = MFMA32(v0, pf0, o[d]); o[d] = MFMA32(v1, pf1, o[d]); o[d] = MFMA32(v2, pf2, o[d]); o[d] = MFMA32(v3, pf3, o[d]);
;             }
;         }
;         if (hasn) ATT_STORE(hh ^ 1, hh ^ 1);
;         if (lane == 0) flags[hh * 8 + wid] = wdone ? 1u : 0u;
;         __syncthreads();
;         if (!hasn) { fin = true; break; }
;         { const unsigned f = flags[hh * 8 + (lane & 7)]; if (__all(f != 0u)) { fin = true; break; } }
.LBB0_427:
	ds_read_b128 v[212:215], v163 offset:36864
	ds_read_b128 v[216:219], v163 offset:36896
	ds_read_b128 v[220:223], v163 offset:36928
	ds_read_b128 v[224:227], v163 offset:36960
	ds_read_b128 v[228:231], v163 offset:41472
	ds_read_b128 v[232:235], v163 offset:41504
	v_exp_f32_e32 v80, v80
	v_exp_f32_e32 v81, v81
	v_exp_f32_e32 v82, v82
	v_exp_f32_e32 v83, v83
	v_exp_f32_e32 v84, v84
	v_exp_f32_e32 v85, v85
	v_exp_f32_e32 v86, v86
	v_exp_f32_e32 v87, v87
	v_cvt_pk_bf16_f32 v196, v80, v81
	v_cvt_pk_bf16_f32 v197, v82, v83
	v_cvt_pk_bf16_f32 v198, v84, v85
	v_cvt_pk_bf16_f32 v199, v86, v87
	s_waitcnt lgkmcnt(5)
	s_nop 0
	v_mfma_f32_32x32x16_bf16 v[64:79], v[212:215], v[196:199], v[64:79]
	ds_read_b128 v[212:215], v163 offset:41536
	v_exp_f32_e32 v88, v88
	v_exp_f32_e32 v89, v89
	v_exp_f32_e32 v90, v90
	v_exp_f32_e32 v91, v91
	v_exp_f32_e32 v92, v92
	v_exp_f32_e32 v93, v93
	v_exp_f32_e32 v94, v94
	v_exp_f32_e32 v95, v95
	v_cvt_pk_bf16_f32 v200, v88, v89
	v_cvt_pk_bf16_f32 v201, v90, v91
	v_cvt_pk_bf16_f32 v202, v92, v93
	v_cvt_pk_bf16_f32 v203, v94, v95
	s_waitcnt lgkmcnt(5)
	s_nop 0
	v_mfma_f32_32x32x16_bf16 v[64:79], v[216:219], v[200:203], v[64:79]
	ds_read_b128 v[216:219], v163 offset:41568
	v_exp_f32_e32 v96, v96
	v_exp_f32_e32 v97, v97
	v_exp_f32_e32 v98, v98
	v_exp_f32_e32 v99, v99
	v_exp_f32_e32 v100, v100
	v_exp_f32_e32 v101, v101
	v_exp_f32_e32 v102, v102
	v_exp_f32_e32 v103, v103
	v_cvt_pk_bf16_f32 v204, v96, v97
	v_cvt_pk_bf16_f32 v205, v98, v99
	v_cvt_pk_bf16_f32 v206, v100, v101
	v_cvt_pk_bf16_f32 v207, v102, v103
	s_waitcnt lgkmcnt(5)
	s_nop 0
	v_mfma_f32_32x32x16_bf16 v[64:79], v[220:223], v[204:207], v[64:79]
	ds_read_b128 v[220:223], v163 offset:46080
	v_exp_f32_e32 v104, v104
	v_exp_f32_e32 v105, v105
	v_exp_f32_e32 v106, v106
	v_exp_f32_e32 v107, v107
	v_exp_f32_e32 v108, v108
	v_exp_f32_e32 v109, v109
	v_exp_f32_e32 v110, v110
	v_exp_f32_e32 v111, v111
	v_cvt_pk_bf16_f32 v208, v104, v105
	v_cvt_pk_bf16_f32 v209, v106, v107
	v_cvt_pk_bf16_f32 v210, v108, v109
	v_cvt_pk_bf16_f32 v211, v110, v111
	s_waitcnt lgkmcnt(5)
	s_nop 0
	v_mfma_f32_32x32x16_bf16 v[64:79], v[224:227], v[208:211], v[64:79]
	ds_read_b128 v[224:227], v163 offset:46112
	s_waitcnt lgkmcnt(5)
	v_mfma_f32_32x32x16_bf16 v[48:63], v[228:231], v[196:199], v[48:63]
	ds_read_b128 v[228:231], v163 offset:46144
	v_add_f32_e32 v170, v80, v96
	v_add_f32_e32 v171, v81, v97
	v_add_f32_e32 v172, v82, v98
	s_waitcnt lgkmcnt(5)
	v_mfma_f32_32x32x16_bf16 v[48:63], v[232:235], v[200:203], v[48:63]
	ds_read_b128 v[232:235], v163 offset:46176
	v_add_f32_e32 v173, v83, v99
	v_add_f32_e32 v174, v84, v100
	v_add_f32_e32 v175, v85, v101
	s_waitcnt lgkmcnt(5)
	v_mfma_f32_32x32x16_bf16 v[48:63], v[212:215], v[204:207], v[48:63]
	ds_read_b128 v[212:215], v163 offset:50688
	v_add_f32_e32 v176, v86, v102
	v_add_f32_e32 v177, v87, v103
	v_add_f32_e32 v170, v170, v174
	s_waitcnt lgkmcnt(5)
	v_mfma_f32_32x32x16_bf16 v[48:63], v[216:219], v[208:211], v[48:63]
	ds_read_b128 v[216:219], v163 offset:50720
	v_add_f32_e32 v171, v171, v175
	v_add_f32_e32 v172, v172, v176
	v_add_f32_e32 v173, v173, v177
	s_waitcnt lgkmcnt(5)
	v_mfma_f32_32x32x16_bf16 v[32:47], v[220:223], v[196:199], v[32:47]
	ds_read_b128 v[220:223], v163 offset:50752
	v_add_f32_e32 v174, v88, v104
	v_add_f32_e32 v175, v89, v105
	v_add_f32_e32 v176, v90, v106
	s_waitcnt lgkmcnt(5)
	v_mfma_f32_32x32x16_bf16 v[32:47], v[224:227], v[200:203], v[32:47]
	ds_read_b128 v[224:227], v163 offset:50784
	v_add_f32_e32 v177, v91, v107
	v_add_f32_e32 v170, v170, v174
	v_add_f32_e32 v171, v171, v175
	s_waitcnt lgkmcnt(5)
	v_mfma_f32_32x32x16_bf16 v[32:47], v[228:231], v[204:207], v[32:47]
	v_add_f32_e32 v172, v172, v176
	v_add_f32_e32 v173, v173, v177
	v_add_f32_e32 v174, v92, v108
	s_waitcnt lgkmcnt(4)
	v_mfma_f32_32x32x16_bf16 v[32:47], v[232:235], v[208:211], v[32:47]
	v_add_f32_e32 v175, v93, v109
	v_add_f32_e32 v176, v94, v110
	v_add_f32_e32 v177, v95, v111
	s_waitcnt lgkmcnt(3)
	v_mfma_f32_32x32x16_bf16 v[16:31], v[212:215], v[196:199], v[16:31]
	v_add_f32_e32 v170, v170, v174
	v_add_f32_e32 v171, v171, v175
	v_add_f32_e32 v172, v172, v176
	s_waitcnt lgkmcnt(2)
	v_mfma_f32_32x32x16_bf16 v[16:31], v[216:219], v[200:203], v[16:31]
	v_add_f32_e32 v173, v173, v177
	v_add_f32_e32 v170, v170, v171
	v_add_f32_e32 v172, v172, v173
	s_waitcnt lgkmcnt(1)
	v_mfma_f32_32x32x16_bf16 v[16:31], v[220:223], v[204:207], v[16:31]
	v_add_f32_e32 v170, v170, v172
	v_add_f32_e32 v168, v168, v170
	v_subrev_u32_e32 v15, s8, v167
	s_waitcnt lgkmcnt(0)
	v_mfma_f32_32x32x16_bf16 v[16:31], v[224:227], v[208:211], v[16:31]
	v_cvt_f32_i32_e32 v15, v15
	v_fma_f32 v0, -v142, v15, v161
	v_add_f32_e32 v15, 0xc2000000, v14
	v_cmp_lt_f32_e32 vcc, v0, v15
	s_cmp_eq_u64 vcc, exec
	s_cselect_b64 s[58:59], -1, 0
	s_mov_b64 s[6:7], 0
.LBB0_428:
	s_cmp_lg_u32 s89, 0
	s_cselect_b64 s[60:61], -1, 0
	s_cmp_eq_u32 s89, 0
	s_cbranch_scc1 .LBB0_430
.LBB0_430:
	s_and_saveexec_b64 s[62:63], s[4:5]
	s_cbranch_execz .LBB0_396
	v_cndmask_b32_e64 v0, 0, 1, s[58:59]
	s_waitcnt vmcnt(5)
	v_mov_b32_e32 v2, s90
	ds_write_b32 v2, v0 offset:55328
	s_branch .LBB0_396
